# weight conversion without LDS; prologue converts layer 0 only, layers 1-3 converted at grid-barrier sites of the previous layer (sc1 stores + ready counter)
# speedup vs baseline: 1.0984x; 1.0322x over previous
; __device__ void prologue_phase(char* lds, const Params& p) {
;     ...
;     for (int t = blockIdx.x; t < nt_in + nt_out; t += gridDim.x) {
;         const float* W; bf16_t* Wt; const float* g; int N, k0, n0, no0;
;         if (t < nt_in) {
;             const int l = t >> 10, rem = t & 1023; k0 = (rem >> 6) * 64; n0 = (rem & 63) * 64;
;             W = p.w_in + (size_t)l * 1024 * 4096; N = 4096; Wt = p.wi_t + (size_t)l * 4096 * 1024; g = p.norm_g + l * 1024; no0 = perm_col(n0);
;         } else {
;             const int t2 = t - nt_in; const int l = t2 >> 8, rem = t2 & 255; k0 = (rem >> 4) * 64; n0 = (rem & 15) * 64;
;             W = p.w_out + (size_t)l * 1024 * 1024; N = 1024; Wt = p.wo_t + (size_t)l * 1024 * 1024; g = nullptr; no0 = n0;
;         }
;         {
;             const int i = tid >> 4, j4 = tid & 15;
; #pragma unroll
;             for (int ps = 0; ps < 2; ++ps) {
;                 const int kk = i + 32 * ps;
;                 const f32x4 v = *(const f32x4*)(W + (size_t)(k0 + kk) * N + no0 + 4 * j4);
;                 const float gg = g ? g[k0 + kk] : 1.0f;
;                 tile[kk * 65 + 4 * j4 + 0] = v[0] * gg; tile[kk * 65 + 4 * j4 + 1] = v[1] * gg;
;                 tile[kk * 65 + 4 * j4 + 2] = v[2] * gg; tile[kk * 65 + 4 * j4 + 3] = v[3] * gg;
;             }
;         }
;         __syncthreads();
;         {
;             const int j = tid >> 3, i8 = tid & 7;
;             float v[8];
; #pragma unroll
;             for (int e = 0; e < 8; ++e) v[e] = tile[(8 * i8 + e) * 65 + j];
;             u32x4 w; w.x = cvt_pk_bf16(v[0], v[1]); w.y = cvt_pk_bf16(v[2], v[3]); w.z = cvt_pk_bf16(v[4], v[5]); w.w = cvt_pk_bf16(v[6], v[7]);
;             *(u32x4*)(Wt + (size_t)(n0 + j) * 1024 + k0 + 8 * i8) = w;
;         }
;     ...
;     for (int row = blockIdx.x * 8 + wid; row < NTOK; row += gridDim.x * 8) {
;         float ss = 0.f;
; #pragma unroll
;         for (int i = 0; i < 4; ++i) {
;             const int c = 4 * lane + 256 * i;
;             const f32x4 v = *(const f32x4*)(p.x + (size_t)row * 1024 + c);
;             ss += v[0] * v[0] + v[1] * v[1] + v[2] * v[2] + v[3] * v[3];
;             u32x2 w; w.x = cvt_pk_bf16(v[0], v[1]); w.y = cvt_pk_bf16(v[2], v[3]);
;             *(u32x2*)(p.xb + (size_t)row * 1024 + c) = w;
;         }
; #pragma unroll
;         for (int s = 32; s >= 1; s >>= 1) ss += __shfl_xor(ss, s);
.LBB0_17:
	s_or_b64 exec, exec, s[0:1]
	v_mov_b32_e32 v13, v245
	s_mov_b32 s23, 0
	s_mov_b32 s39, 0
	v_readfirstlane_b32 s38, v245
	s_lshr_b32 s38, s38, 6
	v_readlane_b32 s34, v254, 0
	v_readlane_b32 s35, v254, 1
	s_load_dwordx4 s[28:31], s[34:35], 0x8
	s_load_dwordx2 s[32:33], s[34:35], 0x18
	s_load_dwordx4 s[40:43], s[34:35], 0x60
	v_and_b32_e32 v190, 63, v245
	v_lshrrev_b32_e32 v191, 3, v190
	v_and_b32_e32 v190, 7, v190
	v_lshlrev_b32_e32 v186, 17, v191
	v_lshl_add_u32 v186, v190, 4, v186
	v_lshlrev_b32_e32 v187, 13, v190
	v_lshl_add_u32 v187, v191, 4, v187
	v_lshlrev_b32_e32 v188, 5, v191
	v_lshlrev_b32_e32 v189, 15, v191
	v_lshl_add_u32 v189, v190, 2, v189
	v_lshlrev_b32_e32 v192, 11, v190
	v_lshl_add_u32 v192, v191, 4, v192
	s_lshr_b32 s44, s84, 7
	s_lshl_b32 s46, s38, 1
	s_add_i32 s44, s44, s46
	s_and_b32 s45, s84, 0x7f
	s_lshl_b32 s46, s45, 5
	s_mov_b32 s38, 0
	s_cmpk_ge_u32 s46, 0x400
	s_cselect_b32 s38, 0x200, s38
	s_cmpk_ge_u32 s46, 0x800
	s_cselect_b32 s38, 0x400, s38
	s_cmpk_ge_u32 s46, 0xc00
	s_cselect_b32 s38, 0xfffff800, s38
	s_cmpk_ge_u32 s46, 0xe00
	s_cselect_b32 s38, 0xfffffc00, s38
	s_add_i32 s38, s46, s38
	s_waitcnt lgkmcnt(0)
	s_lshl_b32 s38, s38, 2
	s_lshl_b32 s34, s39, 24
	s_add_u32 s38, s38, s34
	s_lshl_b32 s34, s44, 20
	s_add_u32 s38, s38, s34
	s_add_u32 s30, s30, s38
	s_addc_u32 s31, s31, 0
	s_lshl_b32 s34, s39, 12
	s_lshl_b32 s35, s44, 8
	s_add_i32 s34, s34, s35
	s_add_u32 s28, s28, s34
	s_addc_u32 s29, s29, 0
	s_lshl_b32 s34, s39, 23
	s_lshl_b32 s35, s46, 11
	s_add_u32 s34, s34, s35
	s_lshl_b32 s35, s44, 7
	s_add_u32 s34, s34, s35
	s_addk_i32 s34, 0x1000
	s_add_u32 s24, s40, s34
	s_addc_u32 s25, s41, 0
	s_lshl_b32 s34, s39, 22
	s_lshl_b32 s35, s44, 18
	s_add_u32 s34, s34, s35
	s_lshl_b32 s35, s45, 5
	s_add_u32 s34, s34, s35
	s_add_u32 s32, s32, s34
	s_addc_u32 s33, s33, 0
	s_lshl_b32 s34, s39, 21
	s_lshl_b32 s35, s45, 14
	s_add_u32 s34, s34, s35
	s_lshl_b32 s35, s44, 7
	s_add_u32 s34, s34, s35
	s_add_u32 s26, s42, s34
	s_addc_u32 s27, s43, 0
	global_load_dwordx4 v[104:107], v188, s[28:29]
	global_load_dwordx4 v[108:111], v188, s[28:29] offset:16
	global_load_dwordx4 v[72:75], v186, s[30:31]
	s_add_u32 s30, s30, 0x4000
	s_addc_u32 s31, s31, 0
	global_load_dwordx4 v[76:79], v186, s[30:31]
	s_add_u32 s30, s30, 0x4000
	s_addc_u32 s31, s31, 0
	global_load_dwordx4 v[80:83], v186, s[30:31]
	s_add_u32 s30, s30, 0x4000
	s_addc_u32 s31, s31, 0
	global_load_dwordx4 v[84:87], v186, s[30:31]
	s_add_u32 s30, s30, 0x4000
	s_addc_u32 s31, s31, 0
	global_load_dwordx4 v[88:91], v186, s[30:31]
	s_add_u32 s30, s30, 0x4000
	s_addc_u32 s31, s31, 0
	global_load_dwordx4 v[92:95], v186, s[30:31]
	s_add_u32 s30, s30, 0x4000
	s_addc_u32 s31, s31, 0
	global_load_dwordx4 v[96:99], v186, s[30:31]
	s_add_u32 s30, s30, 0x4000
	s_addc_u32 s31, s31, 0
	global_load_dwordx4 v[100:103], v186, s[30:31]
	global_load_dword v218, v189, s[32:33]
	s_add_u32 s32, s32, 0x1000
	s_addc_u32 s33, s33, 0
	global_load_dword v219, v189, s[32:33]
	s_add_u32 s32, s32, 0x1000
	s_addc_u32 s33, s33, 0
	global_load_dword v220, v189, s[32:33]
	s_add_u32 s32, s32, 0x1000
	s_addc_u32 s33, s33, 0
	global_load_dword v221, v189, s[32:33]
	s_add_u32 s32, s32, 0x1000
	s_addc_u32 s33, s33, 0
	global_load_dword v222, v189, s[32:33]
	s_add_u32 s32, s32, 0x1000
	s_addc_u32 s33, s33, 0
	global_load_dword v223, v189, s[32:33]
	s_add_u32 s32, s32, 0x1000
	s_addc_u32 s33, s33, 0
	global_load_dword v224, v189, s[32:33]
	s_add_u32 s32, s32, 0x1000
	s_addc_u32 s33, s33, 0
	global_load_dword v225, v189, s[32:33]
	s_mov_b32 s23, 1
.Lwc_iskip_p:
.LBB0_42:
	v_ashrrev_i32_e32 v0, 6, v13
	s_lshl_b32 s0, s84, 3
	v_writelane_b32 v254, s0, 3
	v_add_u32_e32 v0, s0, v0
	s_movk_i32 s0, 0x4000
	v_cmp_gt_i32_e32 vcc, s0, v0
	v_mbcnt_lo_u32_b32 v8, -1, 0
	s_and_saveexec_b64 s[0:1], vcc
	s_cbranch_execz .LBB0_47
	v_mbcnt_hi_u32_b32 v2, -1, v8
	v_and_b32_e32 v3, 64, v2
	v_add_u32_e32 v3, 64, v3
	v_xor_b32_e32 v4, 32, v2
	v_cmp_lt_i32_e64 s[6:7], v4, v3
	v_readlane_b32 s10, v254, 0
	v_readlane_b32 s11, v254, 1
	v_cndmask_b32_e64 v4, v2, v4, s[6:7]
	v_lshlrev_b32_e32 v9, 2, v4
	v_xor_b32_e32 v4, 16, v2
	v_cmp_lt_i32_e64 s[6:7], v4, v3
	s_load_dword s2, s[10:11], 0xb8
	s_load_dwordx4 s[12:15], s[10:11], 0x70
	v_cndmask_b32_e64 v4, v2, v4, s[6:7]
	v_lshlrev_b32_e32 v10, 2, v4
	v_xor_b32_e32 v4, 8, v2
	v_cmp_lt_i32_e64 s[6:7], v4, v3
	s_waitcnt lgkmcnt(0)
	s_lshl_b32 s8, s2, 3
	s_load_dwordx2 s[2:3], s[10:11], 0x0
	v_cndmask_b32_e64 v4, v2, v4, s[6:7]
	v_lshlrev_b32_e32 v11, 2, v4
	v_xor_b32_e32 v4, 4, v2
	v_cmp_lt_i32_e64 s[6:7], v4, v3
	v_and_b32_e32 v1, 63, v13
	v_mov_b32_e32 v7, 0
	v_cndmask_b32_e64 v4, v2, v4, s[6:7]
	v_lshlrev_b32_e32 v12, 2, v4
	v_xor_b32_e32 v4, 2, v2
	v_cmp_lt_i32_e64 s[6:7], v4, v3
	v_lshlrev_b32_e32 v6, 2, v1
	v_mov_b32_e32 v5, v7
	v_cndmask_b32_e64 v4, v2, v4, s[6:7]
	v_lshlrev_b32_e32 v13, 2, v4
	v_xor_b32_e32 v4, 1, v2
	v_cmp_lt_i32_e64 s[6:7], v4, v3
	v_mov_b32_e32 v3, v7
	v_cmp_gt_u32_e32 vcc, 16, v1
	v_cndmask_b32_e64 v2, v2, v4, s[6:7]
	v_lshlrev_b32_e32 v14, 2, v2
	v_lshlrev_b32_e32 v2, 4, v1
	v_lshlrev_b32_e32 v4, 3, v1
	v_cmp_eq_u32_e64 s[4:5], 0, v1
	s_waitcnt lgkmcnt(0)
	v_lshl_add_u64 v[2:3], s[2:3], 0, v[2:3]
	v_lshl_add_u64 v[4:5], s[12:13], 0, v[4:5]
	v_lshl_add_u64 v[6:7], s[14:15], 0, v[6:7]
	s_mov_b64 s[2:3], 0
	s_movk_i32 s9, 0x3fff
	s_branch .LBB0_45

; __device__ void prologue_phase(char* lds, const Params& p) {
;     ...
;                 const f32x4 v = *(const f32x4*)(W + (size_t)(k0 + kk) * N + no0 + 4 * j4);
;                 const float gg = g ? g[k0 + kk] : 1.0f;
;                 tile[kk * 65 + 4 * j4 + 0] = v[0] * gg; tile[kk * 65 + 4 * j4 + 1] = v[1] * gg;
;                 tile[kk * 65 + 4 * j4 + 2] = v[2] * gg; tile[kk * 65 + 4 * j4 + 3] = v[3] * gg;
;             }
;         }
;         __syncthreads();
;         {
;             const int j = tid >> 3, i8 = tid & 7;
;             float v[8];
; #pragma unroll
;             for (int e = 0; e < 8; ++e) v[e] = tile[(8 * i8 + e) * 65 + j];
;             u32x4 w; w.x = cvt_pk_bf16(v[0], v[1]); w.y = cvt_pk_bf16(v[2], v[3]); w.z = cvt_pk_bf16(v[4], v[5]); w.w = cvt_pk_bf16(v[6], v[7]);
;             *(u32x4*)(Wt + (size_t)(n0 + j) * 1024 + k0 + 8 * i8) = w;
.LBB0_47:
	s_or_b64 exec, exec, s[0:1]
	s_cmp_eq_u32 s23, 0
	s_cbranch_scc1 .Lwc_cskip_p
	s_waitcnt vmcnt(0)
	v_mul_f32_e32 v72, v72, v104
	v_mul_f32_e32 v73, v73, v104
	v_mul_f32_e32 v74, v74, v104
	v_mul_f32_e32 v75, v75, v104
	v_mul_f32_e32 v76, v76, v105
	v_mul_f32_e32 v77, v77, v105
	v_mul_f32_e32 v78, v78, v105
	v_mul_f32_e32 v79, v79, v105
	v_mul_f32_e32 v80, v80, v106
	v_mul_f32_e32 v81, v81, v106
	v_mul_f32_e32 v82, v82, v106
	v_mul_f32_e32 v83, v83, v106
	v_mul_f32_e32 v84, v84, v107
	v_mul_f32_e32 v85, v85, v107
	v_mul_f32_e32 v86, v86, v107
	v_mul_f32_e32 v87, v87, v107
	v_mul_f32_e32 v88, v88, v108
	v_mul_f32_e32 v89, v89, v108
	v_mul_f32_e32 v90, v90, v108
	v_mul_f32_e32 v91, v91, v108
	v_mul_f32_e32 v92, v92, v109
	v_mul_f32_e32 v93, v93, v109
	v_mul_f32_e32 v94, v94, v109
	v_mul_f32_e32 v95, v95, v109
	v_mul_f32_e32 v96, v96, v110
	v_mul_f32_e32 v97, v97, v110
	v_mul_f32_e32 v98, v98, v110
	v_mul_f32_e32 v99, v99, v110
	v_mul_f32_e32 v100, v100, v111
	v_mul_f32_e32 v101, v101, v111
	v_mul_f32_e32 v102, v102, v111
	v_mul_f32_e32 v103, v103, v111
	v_cvt_pk_bf16_f32 v60, v72, v76
	v_cvt_pk_bf16_f32 v61, v80, v84
	v_cvt_pk_bf16_f32 v62, v88, v92
	v_cvt_pk_bf16_f32 v63, v96, v100
	global_store_dwordx4 v187, v[60:63], s[24:25] offset:-4096 sc1
	v_cvt_pk_bf16_f32 v64, v73, v77
	v_cvt_pk_bf16_f32 v65, v81, v85
	v_cvt_pk_bf16_f32 v66, v89, v93
	v_cvt_pk_bf16_f32 v67, v97, v101
	global_store_dwordx4 v187, v[64:67], s[24:25] offset:-2048 sc1
	v_cvt_pk_bf16_f32 v204, v74, v78
	v_cvt_pk_bf16_f32 v205, v82, v86
	v_cvt_pk_bf16_f32 v206, v90, v94
	v_cvt_pk_bf16_f32 v207, v98, v102
	global_store_dwordx4 v187, v[204:207], s[24:25] offset:0 sc1
	v_cvt_pk_bf16_f32 v208, v75, v79
	v_cvt_pk_bf16_f32 v209, v83, v87
	v_cvt_pk_bf16_f32 v210, v91, v95
	v_cvt_pk_bf16_f32 v211, v99, v103
	global_store_dwordx4 v187, v[208:211], s[24:25] offset:2048 sc1
	v_cvt_pk_bf16_f32 v212, v218, v219
	v_cvt_pk_bf16_f32 v213, v220, v221
	v_cvt_pk_bf16_f32 v214, v222, v223
	v_cvt_pk_bf16_f32 v215, v224, v225
	global_store_dwordx4 v192, v[212:215], s[26:27] sc1
	s_mov_b32 s23, 0
.Lwc_cskip_p:
	s_waitcnt vmcnt(0)
	s_waitcnt lgkmcnt(0)
	s_barrier
	s_mov_b32 s23, 0
	s_mov_b32 s39, 1
	v_readfirstlane_b32 s38, v245
	s_lshr_b32 s38, s38, 6
	s_sub_u32 s38, s38, 1
	s_cmp_gt_u32 s38, 3
	s_cbranch_scc1 .Lwc_iskip_a1
	v_readlane_b32 s34, v254, 0
	v_readlane_b32 s35, v254, 1
	s_load_dwordx4 s[28:31], s[34:35], 0x8
	s_load_dwordx2 s[32:33], s[34:35], 0x18
	s_load_dwordx4 s[40:43], s[34:35], 0x60
	v_and_b32_e32 v190, 63, v245
	v_lshrrev_b32_e32 v191, 3, v190
	v_and_b32_e32 v190, 7, v190
	v_lshlrev_b32_e32 v186, 17, v191
	v_lshl_add_u32 v186, v190, 4, v186
	v_lshlrev_b32_e32 v187, 13, v190
	v_lshl_add_u32 v187, v191, 4, v187
	v_lshlrev_b32_e32 v188, 5, v191
	v_lshlrev_b32_e32 v189, 15, v191
	v_lshl_add_u32 v189, v190, 2, v189
	v_lshlrev_b32_e32 v192, 11, v190
	v_lshl_add_u32 v192, v191, 4, v192
	s_lshr_b32 s44, s84, 7
	s_lshl_b32 s46, s38, 1
	s_add_i32 s44, s44, s46
	s_and_b32 s45, s84, 0x7f
	s_lshl_b32 s46, s45, 5
	s_mov_b32 s38, 0
	s_cmpk_ge_u32 s46, 0x400
	s_cselect_b32 s38, 0x200, s38
	s_cmpk_ge_u32 s46, 0x800
	s_cselect_b32 s38, 0x400, s38
	s_cmpk_ge_u32 s46, 0xc00
	s_cselect_b32 s38, 0xfffff800, s38
	s_cmpk_ge_u32 s46, 0xe00
	s_cselect_b32 s38, 0xfffffc00, s38
	s_add_i32 s38, s46, s38
	s_waitcnt lgkmcnt(0)
	s_lshl_b32 s38, s38, 2
	s_lshl_b32 s34, s39, 24
	s_add_u32 s38, s38, s34
	s_lshl_b32 s34, s44, 20
	s_add_u32 s38, s38, s34
	s_add_u32 s30, s30, s38
	s_addc_u32 s31, s31, 0
	s_lshl_b32 s34, s39, 12
	s_lshl_b32 s35, s44, 8
	s_add_i32 s34, s34, s35
	s_add_u32 s28, s28, s34
	s_addc_u32 s29, s29, 0
	s_lshl_b32 s34, s39, 23
	s_lshl_b32 s35, s46, 11
	s_add_u32 s34, s34, s35
	s_lshl_b32 s35, s44, 7
	s_add_u32 s34, s34, s35
	s_addk_i32 s34, 0x1000
	s_add_u32 s24, s40, s34
	s_addc_u32 s25, s41, 0
	s_lshl_b32 s34, s39, 22
	s_lshl_b32 s35, s44, 18
	s_add_u32 s34, s34, s35
	s_lshl_b32 s35, s45, 5
	s_add_u32 s34, s34, s35
	s_add_u32 s32, s32, s34
	s_addc_u32 s33, s33, 0
	s_lshl_b32 s34, s39, 21
	s_lshl_b32 s35, s45, 14
	s_add_u32 s34, s34, s35
	s_lshl_b32 s35, s44, 7
	s_add_u32 s34, s34, s35
	s_add_u32 s26, s42, s34
	s_addc_u32 s27, s43, 0
	global_load_dwordx4 v[104:107], v188, s[28:29]
	global_load_dwordx4 v[108:111], v188, s[28:29] offset:16
	global_load_dwordx4 v[72:75], v186, s[30:31]
	s_add_u32 s30, s30, 0x4000
	s_addc_u32 s31, s31, 0
	global_load_dwordx4 v[76:79], v186, s[30:31]
	s_add_u32 s30, s30, 0x4000
	s_addc_u32 s31, s31, 0
	global_load_dwordx4 v[80:83], v186, s[30:31]
	s_add_u32 s30, s30, 0x4000
	s_addc_u32 s31, s31, 0
	global_load_dwordx4 v[84:87], v186, s[30:31]
	s_add_u32 s30, s30, 0x4000
	s_addc_u32 s31, s31, 0
	global_load_dwordx4 v[88:91], v186, s[30:31]
	s_add_u32 s30, s30, 0x4000
	s_addc_u32 s31, s31, 0
	global_load_dwordx4 v[92:95], v186, s[30:31]
	s_add_u32 s30, s30, 0x4000
	s_addc_u32 s31, s31, 0
	global_load_dwordx4 v[96:99], v186, s[30:31]
	s_add_u32 s30, s30, 0x4000
	s_addc_u32 s31, s31, 0
	global_load_dwordx4 v[100:103], v186, s[30:31]
	global_load_dword v218, v189, s[32:33]
	s_add_u32 s32, s32, 0x1000
	s_addc_u32 s33, s33, 0
	global_load_dword v219, v189, s[32:33]
	s_add_u32 s32, s32, 0x1000
	s_addc_u32 s33, s33, 0
	global_load_dword v220, v189, s[32:33]
	s_add_u32 s32, s32, 0x1000
	s_addc_u32 s33, s33, 0
	global_load_dword v221, v189, s[32:33]
	s_add_u32 s32, s32, 0x1000
	s_addc_u32 s33, s33, 0
	global_load_dword v222, v189, s[32:33]
	s_add_u32 s32, s32, 0x1000
	s_addc_u32 s33, s33, 0
	global_load_dword v223, v189, s[32:33]
	s_add_u32 s32, s32, 0x1000
	s_addc_u32 s33, s33, 0
	global_load_dword v224, v189, s[32:33]
	s_add_u32 s32, s32, 0x1000
	s_addc_u32 s33, s33, 0
	global_load_dword v225, v189, s[32:33]
	s_mov_b32 s23, 1
.Lwc_iskip_a1:
	s_and_saveexec_b64 s[0:1], s[66:67]
	s_cbranch_execz .LBB0_99
	s_add_i32 s2, 0, 0x23000
	v_readlane_b32 s16, v254, 2
	v_mov_b32_e32 v0, s2
	s_waitcnt vmcnt(0) expcnt(0) lgkmcnt(0)
	ds_read_b32 v2, v0
	s_add_i32 s2, 0, 0x23004
	v_mov_b32_e32 v0, s2
	ds_read_b32 v0, v0
	s_waitcnt lgkmcnt(1)
	v_cmp_ne_u32_e32 vcc, 0, v2
	s_cbranch_vccnz .LBB0_63
	v_readlane_b32 s2, v254, 0
	v_readlane_b32 s3, v254, 1
	s_load_dwordx2 s[6:7], s[2:3], 0xb8
	s_load_dword s5, s[2:3], 0xc0
	s_add_u32 s2, s82, 0x1000
	s_addc_u32 s3, s83, 0
	s_add_u32 s4, s82, 0x1100
	s_waitcnt lgkmcnt(0)
	s_mul_i32 s17, s7, s6
	s_mul_i32 s17, s17, s5
	s_addc_u32 s5, s83, 0
	s_add_u32 s6, s82, 0x1200
	s_addc_u32 s7, s83, 0
	s_add_u32 s8, s82, 0x1300
	s_addc_u32 s9, s83, 0
	s_mov_b32 s18, 1
	v_mov_b32_e32 v17, 0
	s_branch .LBB0_51

; __device__ __forceinline__ unsigned xb_ld(unsigned* p)              { return __hip_atomic_load(p, __ATOMIC_RELAXED, __HIP_MEMORY_SCOPE_AGENT); }
; __device__ __forceinline__ unsigned xb_add(unsigned* p, unsigned v) { return __hip_atomic_fetch_add(p, v, __ATOMIC_RELAXED, __HIP_MEMORY_SCOPE_AGENT); }
; #define XB_SPIN(cond, bar) do { unsigned _sp = 0; while (cond) { __builtin_amdgcn_s_sleep(1); \
;     if ((++_sp & 255u) == 0u) { if (xb_ld(&(bar)[XB_TMO])) break; if (_sp > XB_SPIN_CAP) { atomicAdd(&(bar)[XB_TMO], 1u); break; } } } } while (0)
; __device__ __forceinline__ void xcd_barrier(const XcdBarrier& b) {
;     ...
;     if (threadIdx.x == 0) {
;         unsigned* bar = b.bar;
;         unsigned bx = b.x; asm volatile("" : "+s"(bx));
;         __builtin_amdgcn_s_waitcnt(0);
;         unsigned nloc = b.st[0], nx = b.st[1];
;         if (nloc == 0u) { xcd_barrier_complete(bar, bx, nloc, nx); b.st[0] = nloc; b.st[1] = nx; }
;         const unsigned old = xb_add(&bar[XB_XSUB(bx)], 1u);
;         const unsigned gen = old / nloc;
;         if (old + 1u == (gen + 1u) * nloc) {
;             __builtin_amdgcn_fence(__ATOMIC_RELEASE, "agent");
;             asm volatile("s_waitcnt vmcnt(0)" ::: "memory");
;             const unsigned og = xb_add(&bar[XB_TOP], 1u);
;             const unsigned tg = og / nx;
;             if (og + 1u == (tg + 1u) * nx) xb_add(&bar[XB_TOPGEN], 1u);
;             else XB_SPIN(xb_ld(&bar[XB_TOPGEN]) == tg, bar);
;             __builtin_amdgcn_fence(__ATOMIC_ACQUIRE, "agent");
;             xb_add(&bar[XB_XGEN(bx)], 1u);
;             asm volatile("s_waitcnt vmcnt(0)" ::: "memory");
;         } else {
;             XB_SPIN(xb_ld(&bar[XB_XGEN(bx)]) == gen, bar);
;             __builtin_amdgcn_fence(__ATOMIC_ACQUIRE, "agent");
;             asm volatile("s_waitcnt vmcnt(0)" ::: "memory");
;         }
;     }
;     __syncthreads();
.LBB0_101:
	s_cbranch_execz .Lwc_rskip
	v_readlane_b32 s2, v254, 58
	s_cmp_gt_u32 s2, 2
	s_cbranch_scc1 .Lwc_rskip
	s_add_i32 s2, s2, 1
	s_lshl_b32 s2, s2, 9
	s_mov_b32 s5, 0
	s_waitcnt vmcnt(0)
.Lwc_rspin:
	v_readfirstlane_b32 s4, v60
	s_cmp_ge_u32 s4, s2
	s_cbranch_scc1 .Lwc_rok
	s_sleep 1
	v_mov_b32_e32 v61, 0
	global_load_dword v60, v61, s[82:83] offset:256 sc1
	s_add_u32 s5, s5, 1
	s_waitcnt vmcnt(0)
	s_cmp_lt_u32 s5, 0x100000
	s_cbranch_scc1 .Lwc_rspin
.Lwc_rok:
	s_cmp_eq_u32 s5, 0
	s_cbranch_scc1 .Lwc_rskip
	buffer_inv sc1
	s_waitcnt vmcnt(0)

; __device__ void prologue_phase(char* lds, const Params& p) {
;     ...
;                 const f32x4 v = *(const f32x4*)(W + (size_t)(k0 + kk) * N + no0 + 4 * j4);
;                 const float gg = g ? g[k0 + kk] : 1.0f;
;                 tile[kk * 65 + 4 * j4 + 0] = v[0] * gg; tile[kk * 65 + 4 * j4 + 1] = v[1] * gg;
;                 tile[kk * 65 + 4 * j4 + 2] = v[2] * gg; tile[kk * 65 + 4 * j4 + 3] = v[3] * gg;
;             }
;         }
;         __syncthreads();
;         {
;             const int j = tid >> 3, i8 = tid & 7;
;             float v[8];
; #pragma unroll
;             for (int e = 0; e < 8; ++e) v[e] = tile[(8 * i8 + e) * 65 + j];
;             u32x4 w; w.x = cvt_pk_bf16(v[0], v[1]); w.y = cvt_pk_bf16(v[2], v[3]); w.z = cvt_pk_bf16(v[4], v[5]); w.w = cvt_pk_bf16(v[6], v[7]);
;             *(u32x4*)(Wt + (size_t)(n0 + j) * 1024 + k0 + 8 * i8) = w;
.LBB0_103:
	s_cmp_eq_u32 s23, 0
	s_cbranch_scc1 .Lwc_cskip_a
	s_waitcnt vmcnt(0)
	v_mul_f32_e32 v72, v72, v104
	v_mul_f32_e32 v73, v73, v104
	v_mul_f32_e32 v74, v74, v104
	v_mul_f32_e32 v75, v75, v104
	v_mul_f32_e32 v76, v76, v105
	v_mul_f32_e32 v77, v77, v105
	v_mul_f32_e32 v78, v78, v105
	v_mul_f32_e32 v79, v79, v105
	v_mul_f32_e32 v80, v80, v106
	v_mul_f32_e32 v81, v81, v106
	v_mul_f32_e32 v82, v82, v106
	v_mul_f32_e32 v83, v83, v106
	v_mul_f32_e32 v84, v84, v107
	v_mul_f32_e32 v85, v85, v107
	v_mul_f32_e32 v86, v86, v107
	v_mul_f32_e32 v87, v87, v107
	v_mul_f32_e32 v88, v88, v108
	v_mul_f32_e32 v89, v89, v108
	v_mul_f32_e32 v90, v90, v108
	v_mul_f32_e32 v91, v91, v108
	v_mul_f32_e32 v92, v92, v109
	v_mul_f32_e32 v93, v93, v109
	v_mul_f32_e32 v94, v94, v109
	v_mul_f32_e32 v95, v95, v109
	v_mul_f32_e32 v96, v96, v110
	v_mul_f32_e32 v97, v97, v110
	v_mul_f32_e32 v98, v98, v110
	v_mul_f32_e32 v99, v99, v110
	v_mul_f32_e32 v100, v100, v111
	v_mul_f32_e32 v101, v101, v111
	v_mul_f32_e32 v102, v102, v111
	v_mul_f32_e32 v103, v103, v111
	v_cvt_pk_bf16_f32 v60, v72, v76
	v_cvt_pk_bf16_f32 v61, v80, v84
	v_cvt_pk_bf16_f32 v62, v88, v92
	v_cvt_pk_bf16_f32 v63, v96, v100
	global_store_dwordx4 v187, v[60:63], s[24:25] offset:-4096 sc1
	v_cvt_pk_bf16_f32 v64, v73, v77
	v_cvt_pk_bf16_f32 v65, v81, v85
	v_cvt_pk_bf16_f32 v66, v89, v93
	v_cvt_pk_bf16_f32 v67, v97, v101
	global_store_dwordx4 v187, v[64:67], s[24:25] offset:-2048 sc1
	v_cvt_pk_bf16_f32 v204, v74, v78
	v_cvt_pk_bf16_f32 v205, v82, v86
	v_cvt_pk_bf16_f32 v206, v90, v94
	v_cvt_pk_bf16_f32 v207, v98, v102
	global_store_dwordx4 v187, v[204:207], s[24:25] offset:0 sc1
	v_cvt_pk_bf16_f32 v208, v75, v79
	v_cvt_pk_bf16_f32 v209, v83, v87
	v_cvt_pk_bf16_f32 v210, v91, v95
	v_cvt_pk_bf16_f32 v211, v99, v103
	global_store_dwordx4 v187, v[208:211], s[24:25] offset:2048 sc1
	v_cvt_pk_bf16_f32 v212, v218, v219
	v_cvt_pk_bf16_f32 v213, v220, v221
	v_cvt_pk_bf16_f32 v214, v222, v223
	v_cvt_pk_bf16_f32 v215, v224, v225
	global_store_dwordx4 v192, v[212:215], s[26:27] sc1
	s_mov_b32 s23, 0

; __device__ __forceinline__ void xcd_barrier(const XcdBarrier& b) {
;     ...
;     if (threadIdx.x == 0) {
;         unsigned* bar = b.bar;
;         unsigned bx = b.x; asm volatile("" : "+s"(bx));
;         __builtin_amdgcn_s_waitcnt(0);
;         unsigned nloc = b.st[0], nx = b.st[1];
;         if (nloc == 0u) { xcd_barrier_complete(bar, bx, nloc, nx); b.st[0] = nloc; b.st[1] = nx; }
;         const unsigned old = xb_add(&bar[XB_XSUB(bx)], 1u);
;         const unsigned gen = old / nloc;
;         if (old + 1u == (gen + 1u) * nloc) {
;             __builtin_amdgcn_fence(__ATOMIC_RELEASE, "agent");
;             asm volatile("s_waitcnt vmcnt(0)" ::: "memory");
;             const unsigned og = xb_add(&bar[XB_TOP], 1u);
;             const unsigned tg = og / nx;
;             if (og + 1u == (tg + 1u) * nx) xb_add(&bar[XB_TOPGEN], 1u);
;             else XB_SPIN(xb_ld(&bar[XB_TOPGEN]) == tg, bar);
;             __builtin_amdgcn_fence(__ATOMIC_ACQUIRE, "agent");
;             xb_add(&bar[XB_XGEN(bx)], 1u);
;             asm volatile("s_waitcnt vmcnt(0)" ::: "memory");
;         } else {
;             XB_SPIN(xb_ld(&bar[XB_XGEN(bx)]) == gen, bar);
;             __builtin_amdgcn_fence(__ATOMIC_ACQUIRE, "agent");
;             asm volatile("s_waitcnt vmcnt(0)" ::: "memory");
;         }
;     }
;     __syncthreads();
; __device__ void prologue_phase(char* lds, const Params& p) {
;     ...
;     for (int t = blockIdx.x; t < nt_in + nt_out; t += gridDim.x) {
;         const float* W; bf16_t* Wt; const float* g; int N, k0, n0, no0;
;         if (t < nt_in) {
;             const int l = t >> 10, rem = t & 1023; k0 = (rem >> 6) * 64; n0 = (rem & 63) * 64;
;             W = p.w_in + (size_t)l * 1024 * 4096; N = 4096; Wt = p.wi_t + (size_t)l * 4096 * 1024; g = p.norm_g + l * 1024; no0 = perm_col(n0);
;         } else {
;             const int t2 = t - nt_in; const int l = t2 >> 8, rem = t2 & 255; k0 = (rem >> 4) * 64; n0 = (rem & 15) * 64;
;             W = p.w_out + (size_t)l * 1024 * 1024; N = 1024; Wt = p.wo_t + (size_t)l * 1024 * 1024; g = nullptr; no0 = n0;
;         }
;         {
;             const int i = tid >> 4, j4 = tid & 15;
; #pragma unroll
;             for (int ps = 0; ps < 2; ++ps) {
;                 const int kk = i + 32 * ps;
;                 const f32x4 v = *(const f32x4*)(W + (size_t)(k0 + kk) * N + no0 + 4 * j4);
.LBB0_379:
	s_waitcnt vmcnt(0)
	s_waitcnt vmcnt(63) expcnt(7) lgkmcnt(15)
	s_barrier
	s_mov_b32 s23, 0
	v_readlane_b32 s39, v254, 58
	s_cmp_gt_u32 s39, 2
	s_cbranch_scc1 .Lwc_iskip_s2
	s_add_i32 s39, s39, 1
	v_readfirstlane_b32 s38, v245
	s_lshr_b32 s38, s38, 6
	s_sub_u32 s38, s38, 1
	s_cmp_gt_u32 s38, 3
	s_cbranch_scc1 .Lwc_iskip_s2
	s_add_i32 s38, s38, 4
	v_readlane_b32 s34, v254, 0
	v_readlane_b32 s35, v254, 1
	s_load_dwordx4 s[28:31], s[34:35], 0x8
	s_load_dwordx2 s[32:33], s[34:35], 0x18
	s_load_dwordx4 s[40:43], s[34:35], 0x60
	v_and_b32_e32 v190, 63, v245
	v_lshrrev_b32_e32 v191, 3, v190
	v_and_b32_e32 v190, 7, v190
	v_lshlrev_b32_e32 v186, 17, v191
	v_lshl_add_u32 v186, v190, 4, v186
	v_lshlrev_b32_e32 v187, 13, v190
	v_lshl_add_u32 v187, v191, 4, v187
	v_lshlrev_b32_e32 v188, 5, v191
	v_lshlrev_b32_e32 v189, 15, v191
	v_lshl_add_u32 v189, v190, 2, v189
	v_lshlrev_b32_e32 v192, 11, v190
	v_lshl_add_u32 v192, v191, 4, v192
	s_lshr_b32 s44, s84, 7
	s_lshl_b32 s46, s38, 1
	s_add_i32 s44, s44, s46
	s_and_b32 s45, s84, 0x7f
	s_lshl_b32 s46, s45, 5
	s_mov_b32 s38, 0
	s_cmpk_ge_u32 s46, 0x400
	s_cselect_b32 s38, 0x200, s38
	s_cmpk_ge_u32 s46, 0x800
	s_cselect_b32 s38, 0x400, s38
	s_cmpk_ge_u32 s46, 0xc00
	s_cselect_b32 s38, 0xfffff800, s38
	s_cmpk_ge_u32 s46, 0xe00
	s_cselect_b32 s38, 0xfffffc00, s38
	s_add_i32 s38, s46, s38
	s_waitcnt lgkmcnt(0)
	s_lshl_b32 s38, s38, 2
	s_lshl_b32 s34, s39, 24
	s_add_u32 s38, s38, s34
	s_lshl_b32 s34, s44, 20
	s_add_u32 s38, s38, s34
	s_add_u32 s30, s30, s38
	s_addc_u32 s31, s31, 0
	s_lshl_b32 s34, s39, 12
	s_lshl_b32 s35, s44, 8
	s_add_i32 s34, s34, s35
	s_add_u32 s28, s28, s34
	s_addc_u32 s29, s29, 0
	s_lshl_b32 s34, s39, 23
	s_lshl_b32 s35, s46, 11
	s_add_u32 s34, s34, s35
	s_lshl_b32 s35, s44, 7
	s_add_u32 s34, s34, s35
	s_addk_i32 s34, 0x1000
	s_add_u32 s24, s40, s34
	s_addc_u32 s25, s41, 0
	s_lshl_b32 s34, s39, 22
	s_lshl_b32 s35, s44, 18
	s_add_u32 s34, s34, s35
	s_lshl_b32 s35, s45, 5
	s_add_u32 s34, s34, s35
	s_add_u32 s32, s32, s34
	s_addc_u32 s33, s33, 0
	s_lshl_b32 s34, s39, 21
	s_lshl_b32 s35, s45, 14
	s_add_u32 s34, s34, s35
	s_lshl_b32 s35, s44, 7
	s_add_u32 s34, s34, s35
	s_add_u32 s26, s42, s34
	s_addc_u32 s27, s43, 0
	global_load_dwordx4 v[104:107], v188, s[28:29]
	global_load_dwordx4 v[108:111], v188, s[28:29] offset:16
	global_load_dwordx4 v[72:75], v186, s[30:31]
	s_add_u32 s30, s30, 0x4000
	s_addc_u32 s31, s31, 0
	global_load_dwordx4 v[76:79], v186, s[30:31]
	s_add_u32 s30, s30, 0x4000
	s_addc_u32 s31, s31, 0
	global_load_dwordx4 v[80:83], v186, s[30:31]
	s_add_u32 s30, s30, 0x4000
	s_addc_u32 s31, s31, 0
	global_load_dwordx4 v[84:87], v186, s[30:31]
	s_add_u32 s30, s30, 0x4000
	s_addc_u32 s31, s31, 0
	global_load_dwordx4 v[88:91], v186, s[30:31]
	s_add_u32 s30, s30, 0x4000
	s_addc_u32 s31, s31, 0
	global_load_dwordx4 v[92:95], v186, s[30:31]
	s_add_u32 s30, s30, 0x4000
	s_addc_u32 s31, s31, 0
	global_load_dwordx4 v[96:99], v186, s[30:31]
	s_add_u32 s30, s30, 0x4000
	s_addc_u32 s31, s31, 0
	global_load_dwordx4 v[100:103], v186, s[30:31]
	global_load_dword v218, v189, s[32:33]
	s_add_u32 s32, s32, 0x1000
	s_addc_u32 s33, s33, 0
	global_load_dword v219, v189, s[32:33]
	s_add_u32 s32, s32, 0x1000
	s_addc_u32 s33, s33, 0
	global_load_dword v220, v189, s[32:33]
	s_add_u32 s32, s32, 0x1000
	s_addc_u32 s33, s33, 0
	global_load_dword v221, v189, s[32:33]
	s_add_u32 s32, s32, 0x1000
	s_addc_u32 s33, s33, 0
	global_load_dword v222, v189, s[32:33]
	s_add_u32 s32, s32, 0x1000
	s_addc_u32 s33, s33, 0
	global_load_dword v223, v189, s[32:33]
	s_add_u32 s32, s32, 0x1000
	s_addc_u32 s33, s33, 0
	global_load_dword v224, v189, s[32:33]
	s_add_u32 s32, s32, 0x1000
	s_addc_u32 s33, s33, 0
	global_load_dword v225, v189, s[32:33]
	s_mov_b32 s23, 1
.Lwc_iskip_s2:
	s_and_saveexec_b64 s[0:1], s[66:67]
	s_cbranch_execz .LBB0_431
	v_readlane_b32 s2, v254, 58
	s_cmp_gt_u32 s2, 2
	s_cbranch_scc1 .Lwc_pskip_2
	v_mov_b32_e32 v60, 0
	v_mov_b32_e32 v61, 1
	global_atomic_add v60, v61, s[82:83] offset:256
.Lwc_pskip_2:
	s_cmp_eq_u32 s99, 0
	s_cbranch_scc1 .Lxb_full_1
	v_readlane_b32 s2, v254, 2
	v_mov_b32_e32 v1, 1
	s_lshl_b32 s2, s2, 8
	s_mov_b32 s98, 0
	v_mov_b32_e32 v0, s2
	global_atomic_add v1, v0, v1, s[82:83] offset:1152 sc0
	s_waitcnt vmcnt(0)
	v_lshrrev_b32_e32 v1, 5, v1
	v_add_u32_e32 v1, 1, v1
	v_lshlrev_b32_e32 v1, 5, v1

; __device__ void prologue_phase(char* lds, const Params& p) {
;     ...
;                 const f32x4 v = *(const f32x4*)(W + (size_t)(k0 + kk) * N + no0 + 4 * j4);
;                 const float gg = g ? g[k0 + kk] : 1.0f;
;                 tile[kk * 65 + 4 * j4 + 0] = v[0] * gg; tile[kk * 65 + 4 * j4 + 1] = v[1] * gg;
;                 tile[kk * 65 + 4 * j4 + 2] = v[2] * gg; tile[kk * 65 + 4 * j4 + 3] = v[3] * gg;
;             }
;         }
;         __syncthreads();
;         {
;             const int j = tid >> 3, i8 = tid & 7;
;             float v[8];
; #pragma unroll
;             for (int e = 0; e < 8; ++e) v[e] = tile[(8 * i8 + e) * 65 + j];
;             u32x4 w; w.x = cvt_pk_bf16(v[0], v[1]); w.y = cvt_pk_bf16(v[2], v[3]); w.z = cvt_pk_bf16(v[4], v[5]); w.w = cvt_pk_bf16(v[6], v[7]);
;             *(u32x4*)(Wt + (size_t)(n0 + j) * 1024 + k0 + 8 * i8) = w;
; __global__ void __launch_bounds__(NTHREADS) fwd_megakernel(Params p) {
;     ...
;         { int t0_ = threadIdx.x; asm volatile("" : "+v"(t0_));
;           for (int i = t0_; i < 8 * 465; i += NTHREADS) ((float*)(lds + LDS_RPB_OFF))[i] = p.rpb[(size_t)layer * 8 * 465 + i] * LOG2E;
;           if (t0_ < 128) ((float*)(lds + LDS_SG_OFF))[t0_] = p.subln_g[layer * 128 + t0_];
;           if (t0_ == 0) *(volatile unsigned*)(lds + LDS_PHASE_BYTES + 12) = 0u; }
.LBB0_431:
	s_or_b64 exec, exec, s[0:1]
	s_waitcnt lgkmcnt(0)
	v_mov_b32_e32 v0, v245
	s_movk_i32 s0, 0xe88
	s_barrier
	s_cmp_eq_u32 s23, 0
	s_cbranch_scc1 .Lwc_cskip_s2
	s_waitcnt vmcnt(0)
	v_mul_f32_e32 v72, v72, v104
	v_mul_f32_e32 v73, v73, v104
	v_mul_f32_e32 v74, v74, v104
	v_mul_f32_e32 v75, v75, v104
	v_mul_f32_e32 v76, v76, v105
	v_mul_f32_e32 v77, v77, v105
	v_mul_f32_e32 v78, v78, v105
	v_mul_f32_e32 v79, v79, v105
	v_mul_f32_e32 v80, v80, v106
	v_mul_f32_e32 v81, v81, v106
	v_mul_f32_e32 v82, v82, v106
	v_mul_f32_e32 v83, v83, v106
	v_mul_f32_e32 v84, v84, v107
	v_mul_f32_e32 v85, v85, v107
	v_mul_f32_e32 v86, v86, v107
	v_mul_f32_e32 v87, v87, v107
	v_mul_f32_e32 v88, v88, v108
	v_mul_f32_e32 v89, v89, v108
	v_mul_f32_e32 v90, v90, v108
	v_mul_f32_e32 v91, v91, v108
	v_mul_f32_e32 v92, v92, v109
	v_mul_f32_e32 v93, v93, v109
	v_mul_f32_e32 v94, v94, v109
	v_mul_f32_e32 v95, v95, v109
	v_mul_f32_e32 v96, v96, v110
	v_mul_f32_e32 v97, v97, v110
	v_mul_f32_e32 v98, v98, v110
	v_mul_f32_e32 v99, v99, v110
	v_mul_f32_e32 v100, v100, v111
	v_mul_f32_e32 v101, v101, v111
	v_mul_f32_e32 v102, v102, v111
	v_mul_f32_e32 v103, v103, v111
	v_cvt_pk_bf16_f32 v60, v72, v76
	v_cvt_pk_bf16_f32 v61, v80, v84
	v_cvt_pk_bf16_f32 v62, v88, v92
	v_cvt_pk_bf16_f32 v63, v96, v100
	global_store_dwordx4 v187, v[60:63], s[24:25] offset:-4096 sc1
	v_cvt_pk_bf16_f32 v64, v73, v77
	v_cvt_pk_bf16_f32 v65, v81, v85
	v_cvt_pk_bf16_f32 v66, v89, v93
	v_cvt_pk_bf16_f32 v67, v97, v101
	global_store_dwordx4 v187, v[64:67], s[24:25] offset:-2048 sc1
	v_cvt_pk_bf16_f32 v204, v74, v78
	v_cvt_pk_bf16_f32 v205, v82, v86
	v_cvt_pk_bf16_f32 v206, v90, v94
	v_cvt_pk_bf16_f32 v207, v98, v102
	global_store_dwordx4 v187, v[204:207], s[24:25] offset:0 sc1
	v_cvt_pk_bf16_f32 v208, v75, v79
	v_cvt_pk_bf16_f32 v209, v83, v87
	v_cvt_pk_bf16_f32 v210, v91, v95
	v_cvt_pk_bf16_f32 v211, v99, v103
	global_store_dwordx4 v187, v[208:211], s[24:25] offset:2048 sc1
	v_cvt_pk_bf16_f32 v212, v218, v219
	v_cvt_pk_bf16_f32 v213, v220, v221
	v_cvt_pk_bf16_f32 v214, v222, v223
	v_cvt_pk_bf16_f32 v215, v224, v225
	global_store_dwordx4 v192, v[212:215], s[26:27] sc1
	s_mov_b32 s23, 0
.Lwc_cskip_s2:
	s_nop 0
	v_cmp_gt_i32_e32 vcc, s0, v0
	s_and_saveexec_b64 s[0:1], vcc
	s_cbranch_execz .LBB0_444
	v_max_i32_e32 v1, 0xc88, v0
	v_sub_u32_e32 v1, v1, v0
	v_add_u32_e32 v1, 0x1ff, v1
	s_movk_i32 s2, 0x1ff
	v_cmp_lt_u32_e32 vcc, s2, v1
	s_mov_b64 s[4:5], -1
	v_mov_b32_e32 v4, v0
	s_and_saveexec_b64 s[2:3], vcc
	s_cbranch_execz .LBB0_441
	v_readlane_b32 s4, v254, 58
	v_readlane_b32 s5, v254, 59
	s_mul_i32 s70, s4, 0xe88
	v_readlane_b32 s8, v254, 52
	v_lshrrev_b32_e32 v4, 9, v1
	s_lshl_b64 s[4:5], s[70:71], 2
	v_readlane_b32 s10, v254, 54
	v_add_u32_e32 v2, -1, v4
	v_readlane_b32 s11, v254, 55
	s_add_u32 s4, s10, s4
	v_add_u32_e32 v1, 0x200, v0
	v_lshrrev_b32_e32 v3, 1, v2
	s_addc_u32 s5, s11, s5
	v_add_u32_e32 v5, 1, v3
	v_cmp_lt_u32_e32 vcc, 13, v2
	v_mov_b32_e32 v8, 0
	v_mov_b64_e32 v[2:3], v[0:1]
	v_readlane_b32 s9, v254, 53
	s_and_saveexec_b64 s[6:7], vcc
	s_cbranch_execz .LBB0_437
	v_readlane_b32 s8, v254, 48
	v_and_b32_e32 v6, -8, v5
	s_mov_b32 s10, 0
	v_lshl_add_u32 v7, v0, 2, s8
	s_mov_b64 s[8:9], 0
	v_mov_b64_e32 v[2:3], v[0:1]

; __device__ __forceinline__ unsigned xb_ld(unsigned* p)              { return __hip_atomic_load(p, __ATOMIC_RELAXED, __HIP_MEMORY_SCOPE_AGENT); }
; __device__ __forceinline__ unsigned xb_add(unsigned* p, unsigned v) { return __hip_atomic_fetch_add(p, v, __ATOMIC_RELAXED, __HIP_MEMORY_SCOPE_AGENT); }
; #define XB_SPIN(cond, bar) do { unsigned _sp = 0; while (cond) { __builtin_amdgcn_s_sleep(1); \
;     if ((++_sp & 255u) == 0u) { if (xb_ld(&(bar)[XB_TMO])) break; if (_sp > XB_SPIN_CAP) { atomicAdd(&(bar)[XB_TMO], 1u); break; } } } } while (0)
; __device__ __forceinline__ void xcd_barrier(const XcdBarrier& b) {
;     ...
;     if (threadIdx.x == 0) {
;         unsigned* bar = b.bar;
;         unsigned bx = b.x; asm volatile("" : "+s"(bx));
;         __builtin_amdgcn_s_waitcnt(0);
;         unsigned nloc = b.st[0], nx = b.st[1];
;         if (nloc == 0u) { xcd_barrier_complete(bar, bx, nloc, nx); b.st[0] = nloc; b.st[1] = nx; }
;         const unsigned old = xb_add(&bar[XB_XSUB(bx)], 1u);
;         const unsigned gen = old / nloc;
;         if (old + 1u == (gen + 1u) * nloc) {
;             __builtin_amdgcn_fence(__ATOMIC_RELEASE, "agent");
;             asm volatile("s_waitcnt vmcnt(0)" ::: "memory");
;             const unsigned og = xb_add(&bar[XB_TOP], 1u);
;             const unsigned tg = og / nx;
;             if (og + 1u == (tg + 1u) * nx) xb_add(&bar[XB_TOPGEN], 1u);
;             else XB_SPIN(xb_ld(&bar[XB_TOPGEN]) == tg, bar);
;             __builtin_amdgcn_fence(__ATOMIC_ACQUIRE, "agent");
;             xb_add(&bar[XB_XGEN(bx)], 1u);
;             asm volatile("s_waitcnt vmcnt(0)" ::: "memory");
;         } else {
;             XB_SPIN(xb_ld(&bar[XB_XGEN(bx)]) == gen, bar);
;             __builtin_amdgcn_fence(__ATOMIC_ACQUIRE, "agent");
;             asm volatile("s_waitcnt vmcnt(0)" ::: "memory");
;         }
;     }
;     __syncthreads();
; __global__ void __launch_bounds__(NTHREADS) fwd_megakernel(Params p) {
;     ...
;         xcd_barrier(gb);
.LBB0_547:
	s_or_b64 exec, exec, s[76:77]
	s_waitcnt vmcnt(0)
	v_readlane_b32 s66, v255, 24
	v_readlane_b32 s67, v255, 25
	s_barrier
	s_and_saveexec_b64 s[0:1], s[66:67]
	v_readlane_b32 s72, v255, 26
	v_readlane_b32 s74, v255, 28
	v_readlane_b32 s78, v255, 30
	v_readlane_b32 s80, v255, 32
	v_readlane_b32 s92, v255, 34
	v_readlane_b32 s73, v255, 27
	v_readlane_b32 s75, v255, 29
	v_readlane_b32 s79, v255, 31
	v_readlane_b32 s81, v255, 33
	v_readlane_b32 s93, v255, 35
	s_cbranch_execz .LBB0_599
	v_readlane_b32 s2, v254, 58
	s_cmp_gt_u32 s2, 2
	s_cbranch_scc1 .Lwc_pskip_3
	v_mov_b32_e32 v60, 0
	v_mov_b32_e32 v61, 1
	global_atomic_add v60, v61, s[82:83] offset:256

; __device__ __forceinline__ unsigned xb_ld(unsigned* p)              { return __hip_atomic_load(p, __ATOMIC_RELAXED, __HIP_MEMORY_SCOPE_AGENT); }
; __device__ __forceinline__ unsigned xb_add(unsigned* p, unsigned v) { return __hip_atomic_fetch_add(p, v, __ATOMIC_RELAXED, __HIP_MEMORY_SCOPE_AGENT); }
; #define XB_SPIN(cond, bar) do { unsigned _sp = 0; while (cond) { __builtin_amdgcn_s_sleep(1); \
;     if ((++_sp & 255u) == 0u) { if (xb_ld(&(bar)[XB_TMO])) break; if (_sp > XB_SPIN_CAP) { atomicAdd(&(bar)[XB_TMO], 1u); break; } } } } while (0)
; __device__ __forceinline__ void xcd_barrier(const XcdBarrier& b) {
;     ...
;     if (threadIdx.x == 0) {
;         unsigned* bar = b.bar;
;         unsigned bx = b.x; asm volatile("" : "+s"(bx));
;         __builtin_amdgcn_s_waitcnt(0);
;         unsigned nloc = b.st[0], nx = b.st[1];
;         if (nloc == 0u) { xcd_barrier_complete(bar, bx, nloc, nx); b.st[0] = nloc; b.st[1] = nx; }
;         const unsigned old = xb_add(&bar[XB_XSUB(bx)], 1u);
;         const unsigned gen = old / nloc;
;         if (old + 1u == (gen + 1u) * nloc) {
;             __builtin_amdgcn_fence(__ATOMIC_RELEASE, "agent");
;             asm volatile("s_waitcnt vmcnt(0)" ::: "memory");
;             const unsigned og = xb_add(&bar[XB_TOP], 1u);
;             const unsigned tg = og / nx;
;             if (og + 1u == (tg + 1u) * nx) xb_add(&bar[XB_TOPGEN], 1u);
;             else XB_SPIN(xb_ld(&bar[XB_TOPGEN]) == tg, bar);
;             __builtin_amdgcn_fence(__ATOMIC_ACQUIRE, "agent");
;             xb_add(&bar[XB_XGEN(bx)], 1u);
;             asm volatile("s_waitcnt vmcnt(0)" ::: "memory");
;         } else {
;             XB_SPIN(xb_ld(&bar[XB_XGEN(bx)]) == gen, bar);
;             __builtin_amdgcn_fence(__ATOMIC_ACQUIRE, "agent");
;             asm volatile("s_waitcnt vmcnt(0)" ::: "memory");
;         }
;     }
;     __syncthreads();
; __global__ void __launch_bounds__(NTHREADS) fwd_megakernel(Params p) {
;     ...
;         xcd_barrier(gb);
.LBB0_676:
	s_mov_b64 s[0:1], -1
	s_and_b64 vcc, exec, s[2:3]
	s_mov_b64 s[2:3], -1
	s_cbranch_vccz .LBB0_102
	s_waitcnt vmcnt(0)
	s_waitcnt lgkmcnt(0)
	s_barrier
	s_mov_b32 s23, 0
	v_readlane_b32 s39, v254, 58
	s_cmp_gt_u32 s39, 1
	s_cbranch_scc1 .Lwc_iskip_a4
	s_add_i32 s39, s39, 2
	v_readfirstlane_b32 s38, v245
	s_lshr_b32 s38, s38, 6
	s_sub_u32 s38, s38, 1
	s_cmp_gt_u32 s38, 3
	s_cbranch_scc1 .Lwc_iskip_a4
	v_readlane_b32 s34, v254, 0
	v_readlane_b32 s35, v254, 1
	s_load_dwordx4 s[28:31], s[34:35], 0x8
	s_load_dwordx2 s[32:33], s[34:35], 0x18
	s_load_dwordx4 s[40:43], s[34:35], 0x60
	v_and_b32_e32 v190, 63, v245
	v_lshrrev_b32_e32 v191, 3, v190
	v_and_b32_e32 v190, 7, v190
	v_lshlrev_b32_e32 v186, 17, v191
	v_lshl_add_u32 v186, v190, 4, v186
	v_lshlrev_b32_e32 v187, 13, v190
	v_lshl_add_u32 v187, v191, 4, v187
	v_lshlrev_b32_e32 v188, 5, v191
	v_lshlrev_b32_e32 v189, 15, v191
	v_lshl_add_u32 v189, v190, 2, v189
	v_lshlrev_b32_e32 v192, 11, v190
	v_lshl_add_u32 v192, v191, 4, v192
	s_lshr_b32 s44, s84, 7
	s_lshl_b32 s46, s38, 1
	s_add_i32 s44, s44, s46
	s_and_b32 s45, s84, 0x7f
	s_lshl_b32 s46, s45, 5
	s_mov_b32 s38, 0
	s_cmpk_ge_u32 s46, 0x400
	s_cselect_b32 s38, 0x200, s38
	s_cmpk_ge_u32 s46, 0x800
	s_cselect_b32 s38, 0x400, s38
	s_cmpk_ge_u32 s46, 0xc00
	s_cselect_b32 s38, 0xfffff800, s38
	s_cmpk_ge_u32 s46, 0xe00
	s_cselect_b32 s38, 0xfffffc00, s38
	s_add_i32 s38, s46, s38
	s_waitcnt lgkmcnt(0)
	s_lshl_b32 s38, s38, 2
	s_lshl_b32 s34, s39, 24
	s_add_u32 s38, s38, s34
	s_lshl_b32 s34, s44, 20
	s_add_u32 s38, s38, s34
	s_add_u32 s30, s30, s38
	s_addc_u32 s31, s31, 0
	s_lshl_b32 s34, s39, 12
	s_lshl_b32 s35, s44, 8
	s_add_i32 s34, s34, s35
	s_add_u32 s28, s28, s34
	s_addc_u32 s29, s29, 0
	s_lshl_b32 s34, s39, 23
	s_lshl_b32 s35, s46, 11
	s_add_u32 s34, s34, s35
	s_lshl_b32 s35, s44, 7
	s_add_u32 s34, s34, s35
	s_addk_i32 s34, 0x1000
	s_add_u32 s24, s40, s34
	s_addc_u32 s25, s41, 0
	s_lshl_b32 s34, s39, 22
	s_lshl_b32 s35, s44, 18
	s_add_u32 s34, s34, s35
	s_lshl_b32 s35, s45, 5
	s_add_u32 s34, s34, s35
	s_add_u32 s32, s32, s34
	s_addc_u32 s33, s33, 0
	s_lshl_b32 s34, s39, 21
	s_lshl_b32 s35, s45, 14
	s_add_u32 s34, s34, s35
	s_lshl_b32 s35, s44, 7
	s_add_u32 s34, s34, s35
	s_add_u32 s26, s42, s34
	s_addc_u32 s27, s43, 0
	global_load_dwordx4 v[104:107], v188, s[28:29]
	global_load_dwordx4 v[108:111], v188, s[28:29] offset:16
	global_load_dwordx4 v[72:75], v186, s[30:31]
	s_add_u32 s30, s30, 0x4000
	s_addc_u32 s31, s31, 0
	global_load_dwordx4 v[76:79], v186, s[30:31]
	s_add_u32 s30, s30, 0x4000
	s_addc_u32 s31, s31, 0
	global_load_dwordx4 v[80:83], v186, s[30:31]
	s_add_u32 s30, s30, 0x4000
	s_addc_u32 s31, s31, 0
	global_load_dwordx4 v[84:87], v186, s[30:31]
	s_add_u32 s30, s30, 0x4000
	s_addc_u32 s31, s31, 0
	global_load_dwordx4 v[88:91], v186, s[30:31]
	s_add_u32 s30, s30, 0x4000
	s_addc_u32 s31, s31, 0
	global_load_dwordx4 v[92:95], v186, s[30:31]
	s_add_u32 s30, s30, 0x4000
	s_addc_u32 s31, s31, 0
	global_load_dwordx4 v[96:99], v186, s[30:31]
	s_add_u32 s30, s30, 0x4000
	s_addc_u32 s31, s31, 0
	global_load_dwordx4 v[100:103], v186, s[30:31]
	global_load_dword v218, v189, s[32:33]
	s_add_u32 s32, s32, 0x1000
	s_addc_u32 s33, s33, 0
	global_load_dword v219, v189, s[32:33]
	s_add_u32 s32, s32, 0x1000
	s_addc_u32 s33, s33, 0
	global_load_dword v220, v189, s[32:33]
	s_add_u32 s32, s32, 0x1000
	s_addc_u32 s33, s33, 0
	global_load_dword v221, v189, s[32:33]
	s_add_u32 s32, s32, 0x1000
	s_addc_u32 s33, s33, 0
	global_load_dword v222, v189, s[32:33]
	s_add_u32 s32, s32, 0x1000
	s_addc_u32 s33, s33, 0
	global_load_dword v223, v189, s[32:33]
	s_add_u32 s32, s32, 0x1000
	s_addc_u32 s33, s33, 0
	global_load_dword v224, v189, s[32:33]
	s_add_u32 s32, s32, 0x1000
	s_addc_u32 s33, s33, 0
	global_load_dword v225, v189, s[32:33]
	s_mov_b32 s23, 1
.Lwc_iskip_a4:
	s_and_saveexec_b64 s[0:1], s[66:67]
	s_cbranch_execz .LBB0_101
	v_mov_b32_e32 v61, 0
	global_load_dword v60, v61, s[82:83] offset:256 sc1
	s_cmp_eq_u32 s99, 0
	s_cbranch_scc1 .Lxb_full_3
	v_readlane_b32 s2, v254, 2
	v_mov_b32_e32 v1, 1
	s_lshl_b32 s2, s2, 8
	s_mov_b32 s98, 0
	v_mov_b32_e32 v0, s2
	global_atomic_add v1, v0, v1, s[82:83] offset:1152 sc0
	s_waitcnt vmcnt(0)
	v_lshrrev_b32_e32 v1, 5, v1
	v_add_u32_e32 v1, 1, v1
	v_lshlrev_b32_e32 v1, 5, v1
